# v29 + GEMM phase prologue: the K-tile 1 staging loads issued together with K-tile 0 (one exposed load round trip per phase instead of two)
# speedup vs baseline: 1.0036x; 1.0014x over previous
; #define PG8_STAGE(bufoff, gbase, voff) do { _Pragma("unroll") for (int _i = 0; _i < 2; ++_i) \
;         __builtin_amdgcn_global_load_lds((const unsigned*)((const char*)(gbase) + (voff)[_i]), (PG8_LAS unsigned*)(lds + (bufoff) + ldsw + _i * 8192), 16, 0, 0); } while (0)
; #define PG8_WAIT_V(n) asm volatile("s_waitcnt vmcnt(" #n ")" ::: "memory")
; #define PG8_BAR __builtin_amdgcn_s_barrier()
; template <class Epi, class Sched, bool ALIGN_EPI = false, bool SP2 = false>
; __device__ __forceinline__ void gemm_phase(PG8_LAS unsigned char* lds, const Gemm g, const Sched& S, const Epi& E) {
;     ...
;     if constexpr (SP2) {
;         PG8_STAGE(PG8_SB(0, 0), cB, voffB); PG8_STAGE(PG8_SB(0, 1), cB + hstep, voffB); PG8_STAGE(PG8_SA(0, 0), cA, voffA); PG8_STAGE(PG8_SA(0, 1), cA + hstep, voffA);
;         if (wr == 1) PG8_BAR;
;         PG8_WAIT_V(2); PG8_BAR;
;         PG8_STAGE(PG8_SB(1, 0), cB + kstep, voffB); PG8_STAGE(PG8_SA(1, 0), cA + kstep, voffA); PG8_STAGE(PG8_SB(1, 1), cB + hstep + kstep, voffB);
;         PG8_WAIT_V(6); PG8_BAR;
.LBB0_297:
	s_add_i32 m0, s47, 0x18000
	v_lshl_add_u64 v[0:1], v[0:1], 0, s[94:95]
	global_load_lds_dwordx4 v[0:1], off
	v_lshl_add_u64 v[0:1], v[2:3], 0, s[94:95]
	s_add_i32 m0, s47, 0x1a000
	s_add_i32 s52, s47, 0x8000
	global_load_lds_dwordx4 v[0:1], off
	v_lshl_add_u64 v[0:1], v[8:9], 0, s[94:95]
	s_mov_b32 m0, s52
	s_add_i32 s53, s47, 0xa000
	global_load_lds_dwordx4 v[0:1], off
	v_lshl_add_u64 v[0:1], v[10:11], 0, s[94:95]
	s_mov_b32 m0, s53
	s_lshr_b32 s51, s37, 6
	global_load_lds_dwordx4 v[0:1], off
	s_add_i32 m0, s47, 0x1c000
	v_lshl_add_u64 v[0:1], v[4:5], 0, s[94:95]
	global_load_lds_dwordx4 v[0:1], off
	v_lshl_add_u64 v[0:1], v[6:7], 0, s[94:95]
	s_add_i32 m0, s47, 0x1e000
	s_lshl_b32 s0, s0, 12
	global_load_lds_dwordx4 v[0:1], off
	s_waitcnt vmcnt(8)
	s_barrier
	s_lshl_b32 s1, s1, 13
	s_and_b32 s0, s0, 0x3000
	s_add_i32 s54, s51, -2
	s_cmpk_lt_u32 s6, 0x100
	s_cselect_b64 s[22:23], -1, 0
	s_lshl_b32 s57, s36, 3
	v_cvt_f32_u32_e32 v0, s57
	v_and_b32_e32 v19, 15, v18
	v_and_b32_e32 v20, 48, v18
	v_lshlrev_b32_e32 v18, 2, v18
	v_rcp_iflag_f32_e32 v0, v0
	v_lshlrev_b32_e32 v19, 6, v19
	v_and_b32_e32 v18, 32, v18
	v_or_b32_e32 v21, v19, v20
	v_mul_f32_e32 v0, 0x4f7ffffe, v0
	v_cvt_u32_f32_e32 v0, v0
	v_bitop3_b32 v19, v19, v18, v20 bitop3:0x36
	v_bitop3_b32 v18, v21, s1, v18 bitop3:0xde
	v_or_b32_e32 v179, s0, v19
	s_sub_i32 s0, 0, s57
	v_readfirstlane_b32 s1, v0
	v_add_u32_e32 v0, v17, v15
	s_waitcnt vmcnt(6)
	s_mul_i32 s0, s0, s1
	v_add_lshl_u32 v176, v0, v16, 1
	v_add_u32_e32 v0, v14, v12
	s_mul_hi_u32 s0, s1, s0
	v_lshl_add_u64 v[168:169], s[88:89], 0, v[176:177]
	v_add_lshl_u32 v176, v0, v13, 1
	s_ashr_i32 s55, s33, 31
	s_mov_b32 s17, s89
	s_lshl_b32 s56, s36, 4
	s_mov_b32 s58, 0
	s_add_i32 s59, s1, s0
	v_lshl_add_u64 v[170:171], s[88:89], 0, v[176:177]
	v_add_u32_e32 v228, 0, v18
	s_barrier
	s_branch .LBB0_300
